# v18 + branch-A mid-step barrier and first V pre-read moved before the 7th QK MFMA
# speedup vs baseline: 1.0181x; 1.0034x over previous
; #define SBAR() __builtin_amdgcn_sched_barrier(0)
; __device__ __forceinline__ s16x4 vtr(lds_cptr p) { return __builtin_bit_cast(s16x4, __builtin_amdgcn_ds_read_tr16_b64_v4i16((__attribute__((address_space(3))) v4i16_t*)p)); }
; #define PIN(x) asm volatile("" : "+v"(x))
; __device__ __forceinline__ void add_bias(f32x16& p0, f32x16& p1, const float* tb, int relb, int hi) {
;   const float* t = tb + relb + 4 * hi;
; #pragma unroll
;   for (int r = 0; r < 16; ++r) { p0[r] += t[(r & 3) + 8 * (r >> 2)]; p1[r] += t[32 + (r & 3) + 8 * (r >> 2)]; }
; }
; template <int DK, bool NOMAX> ...
;     ...
;   for (int d0 = 0; d0 < NS; ++d0) {
;     if (d0 == 0) { c0 = __builtin_amdgcn_mfma_f32_32x32x16_bf16(kf[0][0], qr[0], f32x16{}, 0, 0, 0); c1 = __builtin_amdgcn_mfma_f32_32x32x16_bf16(kf[0][1], qr[0], f32x16{}, 0, 0, 0); }
;     else { c0 = __builtin_amdgcn_mfma_f32_32x32x16_bf16(kf[d0 & 1][0], qr[d0], c0, 0, 0, 0); c1 = __builtin_amdgcn_mfma_f32_32x32x16_bf16(kf[d0 & 1][1], qr[d0], c1, 0, 0, 0); }
;     if (d0 + 2 < NS) KRD_(d0 & 1, d0 + 2);
;     if constexpr (NOMAX) { }
;     else {
; #pragma unroll
;     for (int r = d0 * RPS; r < (d0 + 1) * RPS; ++r) { p1[r] = __builtin_amdgcn_exp2f(p1[r]); psa += p0[r]; }
;     if (d0 > 0) {
; #pragma unroll
;       for (int r = (d0 - 1) * RPS; r < d0 * RPS; ++r) psb += p1[r]; } }
;     if constexpr (NOMAX) {
;       if (d0 == NS / 4 - 1) { PK4R(p0, 0, pa[0]); PIN(pa[0]); }
;       if (d0 == NS / 2 - 1) { PK4R(p0, 8, pa[1]); PIN(pa[1]); }
;       if (d0 == 3 * NS / 4 - 1) { PK4R(p1, 0, pa[2]); PIN(pa[2]); }
;       if (d0 == NS - 1) { PK4R(p1, 8, pa[3]); PIN(pa[3]); }
;     } else {
;     if (d0 == NS / 2 - 1) { PK4R(p0, 0, pa[0]); PIN(pa[0]); }
;     if (d0 == NS / 2) { PK4R(p0, 8, pa[1]); PIN(pa[1]); }
;     if (d0 == NS - 1) { PK4R(p1, 0, pa[2]); PIN(pa[2]); }
;     }
;     if (d0 == NS - 1) {
;       vl[0] = vtr(vp + v_rd_off(0, 0, 0)); vh[0] = vtr(vp + v_rd_off(0, 0, 1)); vl[1] = vtr(vp + v_rd_off(1, 0, 0)); vh[1] = vtr(vp + v_rd_off(1, 0, 1)); }
;     PIN(p1); PIN(psa); PIN(psb);
;     SBAR();
;   }
.LBB0_220:
	s_mov_b32 s6, s96
	s_mov_b32 s96, s4
	s_add_i32 s4, s63, 0xffff4000
	s_and_b32 s59, s4, 0xc000
	s_add_i32 s4, s59, 0
	v_add_u32_e32 v213, s96, v187
	s_waitcnt lgkmcnt(0)
	v_mfma_f32_32x32x16_bf16 v[128:143], v[116:119], v[156:159], 0
	v_add_u32_e32 v0, s4, v207
	ds_read_b128 v[2:5], v0
	ds_read_b128 v[164:167], v0 offset:4096
	v_cvt_pk_bf16_f32 v96, v96, v97
	v_cvt_pk_bf16_f32 v97, v98, v99
	v_cvt_pk_bf16_f32 v98, v100, v101
	v_cvt_pk_bf16_f32 v99, v102, v103
	v_mfma_f32_32x32x16_bf16 v[112:127], v[112:115], v[156:159], 0
	v_permlane32_swap_b32_e32 v96, v98
	v_permlane32_swap_b32_e32 v97, v99
	v_mfma_f32_32x32x16_bf16 v[128:143], v[10:13], v[152:155], v[128:143]
	v_mfma_f32_32x32x16_bf16 v[112:127], v[6:9], v[152:155], v[112:127]
	v_add_u32_e32 v6, s4, v208
	ds_read_b128 v[100:103], v6
	ds_read_b128 v[214:217], v6 offset:4096
	v_cvt_pk_bf16_f32 v10, v104, v105
	v_cvt_pk_bf16_f32 v11, v106, v107
	v_cvt_pk_bf16_f32 v12, v108, v109
	v_cvt_pk_bf16_f32 v13, v110, v111
	s_nop 0
	v_permlane32_swap_b32_e32 v10, v12
	v_permlane32_swap_b32_e32 v11, v13
	s_waitcnt lgkmcnt(3)
	v_mfma_f32_32x32x16_bf16 v[128:143], v[2:5], v[148:151], v[128:143]
	v_cvt_pk_bf16_f32 v6, v80, v81
	v_cvt_pk_bf16_f32 v7, v82, v83
	v_cvt_pk_bf16_f32 v8, v84, v85
	v_cvt_pk_bf16_f32 v9, v86, v87
	s_nop 0
	v_permlane32_swap_b32_e32 v6, v8
	s_waitcnt lgkmcnt(2)
	v_mfma_f32_32x32x16_bf16 v[112:127], v[164:167], v[148:151], v[112:127]
	v_permlane32_swap_b32_e32 v7, v9
	s_nop 0
	v_cvt_pk_bf16_f32 v2, v88, v89
	v_cvt_pk_bf16_f32 v3, v90, v91
	v_cvt_pk_bf16_f32 v4, v92, v93
	v_cvt_pk_bf16_f32 v5, v94, v95
	s_cmpk_gt_i32 s97, 0x7b
	s_cbranch_scc1 .Lmy_mb0_a1_1
	s_waitcnt vmcnt(3) lgkmcnt(0)
	s_barrier
.Lmy_mbj_a1_1:
	ds_read_b64_tr_b16 v[104:105], v213
	ds_read_b64_tr_b16 v[106:107], v213 offset:2048
	v_mfma_f32_32x32x16_bf16 v[128:143], v[100:103], v[144:147], v[128:143]
	v_permlane32_swap_b32_e32 v2, v4
	v_permlane32_swap_b32_e32 v3, v5
	ds_read_b64_tr_b16 v[100:101], v213 offset:512
	ds_read_b64_tr_b16 v[102:103], v213 offset:2560
	s_waitcnt lgkmcnt(4)
	v_mfma_f32_32x32x16_bf16 v[112:127], v[214:217], v[144:147], v[112:127]
	v_add_u32_e32 v216, s7, v205
	v_add_u32_e32 v0, 0xffffffa1, v216
	v_cmp_gt_i32_e32 vcc, s67, v0
	v_mov_b32_e32 v215, v199
	s_and_saveexec_b64 s[4:5], vcc
	s_cbranch_execz .LBB0_224
	v_subrev_u32_e32 v0, 64, v216
	v_cmp_lt_i32_e32 vcc, s77, v0
	v_mov_b32_e32 v215, v198
	s_and_saveexec_b64 s[18:19], vcc
	s_cbranch_execz .LBB0_223
	ds_read2_b32 v[80:81], v211 offset1:1
	ds_read2_b32 v[82:83], v211 offset0:2 offset1:3
	ds_read2_b32 v[84:85], v211 offset0:8 offset1:9
	ds_read2_b32 v[86:87], v211 offset0:10 offset1:11
	ds_read2_b32 v[88:89], v211 offset0:16 offset1:17
	ds_read2_b32 v[90:91], v211 offset0:18 offset1:19
	ds_read2_b32 v[92:93], v211 offset0:24 offset1:25
	ds_read2_b32 v[94:95], v211 offset0:26 offset1:27
	ds_read2_b32 v[108:109], v211 offset0:32 offset1:33
	ds_read2_b32 v[110:111], v211 offset0:34 offset1:35
	ds_read2_b32 v[164:165], v211 offset0:40 offset1:41
	ds_read2_b32 v[166:167], v211 offset0:42 offset1:43
	s_waitcnt lgkmcnt(0)
	v_pk_add_f32 v[128:129], v[128:129], v[80:81]
	v_pk_add_f32 v[140:141], v[140:141], v[92:93]
	v_pk_add_f32 v[138:139], v[138:139], v[90:91]
	v_pk_add_f32 v[136:137], v[136:137], v[88:89]
	ds_read2_b32 v[80:81], v211 offset0:48 offset1:49
	ds_read2_b32 v[88:89], v211 offset0:50 offset1:51
	ds_read2_b32 v[90:91], v211 offset0:56 offset1:57
	ds_read2_b32 v[92:93], v211 offset0:58 offset1:59
	v_pk_add_f32 v[142:143], v[142:143], v[94:95]
	v_pk_add_f32 v[134:135], v[134:135], v[86:87]
	v_pk_add_f32 v[132:133], v[132:133], v[84:85]
	v_pk_add_f32 v[130:131], v[130:131], v[82:83]
	v_pk_add_f32 v[112:113], v[112:113], v[108:109]
	s_waitcnt lgkmcnt(0)
	v_pk_add_f32 v[126:127], v[126:127], v[92:93]
	v_pk_add_f32 v[124:125], v[124:125], v[90:91]
	v_pk_add_f32 v[122:123], v[122:123], v[88:89]
	v_pk_add_f32 v[120:121], v[120:121], v[80:81]
	v_pk_add_f32 v[118:119], v[118:119], v[166:167]
	v_pk_add_f32 v[116:117], v[116:117], v[164:165]
	v_pk_add_f32 v[114:115], v[114:115], v[110:111]
	v_mov_b32_e32 v215, 0

; #define SBAR() __builtin_amdgcn_sched_barrier(0)
; __device__ __forceinline__ s16x4 vtr(lds_cptr p) { return __builtin_bit_cast(s16x4, __builtin_amdgcn_ds_read_tr16_b64_v4i16((__attribute__((address_space(3))) v4i16_t*)p)); }
; #define PIN(x) asm volatile("" : "+v"(x))
; __device__ __forceinline__ void add_bias(f32x16& p0, f32x16& p1, const float* tb, int relb, int hi) {
;   const float* t = tb + relb + 4 * hi;
; #pragma unroll
;   for (int r = 0; r < 16; ++r) { p0[r] += t[(r & 3) + 8 * (r >> 2)]; p1[r] += t[32 + (r & 3) + 8 * (r >> 2)]; }
; }
; template <int DK, bool NOMAX> ...
;     ...
;   for (int d0 = 0; d0 < NS; ++d0) {
;     if (d0 == 0) { c0 = __builtin_amdgcn_mfma_f32_32x32x16_bf16(kf[0][0], qr[0], f32x16{}, 0, 0, 0); c1 = __builtin_amdgcn_mfma_f32_32x32x16_bf16(kf[0][1], qr[0], f32x16{}, 0, 0, 0); }
;     else { c0 = __builtin_amdgcn_mfma_f32_32x32x16_bf16(kf[d0 & 1][0], qr[d0], c0, 0, 0, 0); c1 = __builtin_amdgcn_mfma_f32_32x32x16_bf16(kf[d0 & 1][1], qr[d0], c1, 0, 0, 0); }
;     if (d0 + 2 < NS) KRD_(d0 & 1, d0 + 2);
;     if constexpr (NOMAX) { }
;     else {
; #pragma unroll
;     for (int r = d0 * RPS; r < (d0 + 1) * RPS; ++r) { p1[r] = __builtin_amdgcn_exp2f(p1[r]); psa += p0[r]; }
;     if (d0 > 0) {
; #pragma unroll
;       for (int r = (d0 - 1) * RPS; r < d0 * RPS; ++r) psb += p1[r]; } }
;     if constexpr (NOMAX) {
;       if (d0 == NS / 4 - 1) { PK4R(p0, 0, pa[0]); PIN(pa[0]); }
;       if (d0 == NS / 2 - 1) { PK4R(p0, 8, pa[1]); PIN(pa[1]); }
;       if (d0 == 3 * NS / 4 - 1) { PK4R(p1, 0, pa[2]); PIN(pa[2]); }
;       if (d0 == NS - 1) { PK4R(p1, 8, pa[3]); PIN(pa[3]); }
;     } else {
;     if (d0 == NS / 2 - 1) { PK4R(p0, 0, pa[0]); PIN(pa[0]); }
;     if (d0 == NS / 2) { PK4R(p0, 8, pa[1]); PIN(pa[1]); }
;     if (d0 == NS - 1) { PK4R(p1, 0, pa[2]); PIN(pa[2]); }
;     }
;     if (d0 == NS - 1) {
;       vl[0] = vtr(vp + v_rd_off(0, 0, 0)); vh[0] = vtr(vp + v_rd_off(0, 0, 1)); vl[1] = vtr(vp + v_rd_off(1, 0, 0)); vh[1] = vtr(vp + v_rd_off(1, 0, 1)); }
;     PIN(p1); PIN(psa); PIN(psb);
;     SBAR();
;   }
.LBB0_232:
.LBB0_234:
	v_add_u32_e32 v217, s6, v187
	v_mfma_f32_32x32x16_bf16 v[96:111], v[80:83], v[156:159], 0
	v_add_u32_e32 v212, s94, v207
	ds_read_b128 v[2:5], v212
	ds_read_b128 v[218:221], v212 offset:4096
	v_cvt_pk_bf16_f32 v128, v128, v129
	v_cvt_pk_bf16_f32 v129, v130, v131
	v_cvt_pk_bf16_f32 v130, v132, v133
	v_cvt_pk_bf16_f32 v131, v134, v135
	v_mfma_f32_32x32x16_bf16 v[80:95], v[84:87], v[156:159], 0
	v_permlane32_swap_b32_e32 v128, v130
	v_permlane32_swap_b32_e32 v129, v131
	v_mfma_f32_32x32x16_bf16 v[96:111], v[6:9], v[152:155], v[96:111]
	v_add_u32_e32 v6, s94, v208
	ds_read_b128 v[132:135], v6
	ds_read_b128 v[222:225], v6 offset:4096
	v_mfma_f32_32x32x16_bf16 v[80:95], v[10:13], v[152:155], v[80:95]
	v_cvt_pk_bf16_f32 v10, v136, v137
	v_cvt_pk_bf16_f32 v11, v138, v139
	v_cvt_pk_bf16_f32 v12, v140, v141
	v_cvt_pk_bf16_f32 v13, v142, v143
	s_nop 0
	v_permlane32_swap_b32_e32 v10, v12
	v_permlane32_swap_b32_e32 v11, v13
	s_waitcnt lgkmcnt(3)
	v_mfma_f32_32x32x16_bf16 v[96:111], v[2:5], v[148:151], v[96:111]
	v_cvt_pk_bf16_f32 v6, v112, v113
	v_cvt_pk_bf16_f32 v7, v114, v115
	v_cvt_pk_bf16_f32 v8, v116, v117
	v_cvt_pk_bf16_f32 v9, v118, v119
	s_nop 0
	v_permlane32_swap_b32_e32 v6, v8
	s_waitcnt lgkmcnt(2)
	v_mfma_f32_32x32x16_bf16 v[80:95], v[218:221], v[148:151], v[80:95]
	v_permlane32_swap_b32_e32 v7, v9
	s_nop 0
	v_cvt_pk_bf16_f32 v2, v120, v121
	v_cvt_pk_bf16_f32 v3, v122, v123
	v_cvt_pk_bf16_f32 v4, v124, v125
	v_cvt_pk_bf16_f32 v5, v126, v127
	s_cmpk_gt_i32 s97, 0x7c
	s_cbranch_scc1 .Lmy_mb0_a1_2
	s_waitcnt vmcnt(3) lgkmcnt(0)
	s_barrier
.Lmy_mbj_a1_2:
	ds_read_b64_tr_b16 v[136:137], v217
	ds_read_b64_tr_b16 v[138:139], v217 offset:2048
	v_mfma_f32_32x32x16_bf16 v[96:111], v[132:135], v[144:147], v[96:111]
	v_permlane32_swap_b32_e32 v2, v4
	v_permlane32_swap_b32_e32 v3, v5
	ds_read_b64_tr_b16 v[132:133], v217 offset:512
	ds_read_b64_tr_b16 v[134:135], v217 offset:2560
	s_waitcnt lgkmcnt(4)
	v_mfma_f32_32x32x16_bf16 v[80:95], v[222:225], v[144:147], v[80:95]
	v_subrev_u32_e32 v112, 31, v216
	v_cmp_gt_i32_e32 vcc, s67, v112
	v_mov_b32_e32 v212, v199
	s_and_saveexec_b64 s[4:5], vcc
	s_cbranch_execz .LBB0_238
	v_cmp_ge_i32_e32 vcc, s7, v181
	v_mov_b32_e32 v212, v198
	s_and_saveexec_b64 s[94:95], vcc
	s_cbranch_execz .LBB0_237
	ds_read2_b32 v[112:113], v211 offset0:64 offset1:65
	ds_read2_b32 v[114:115], v211 offset0:66 offset1:67
	ds_read2_b32 v[116:117], v211 offset0:72 offset1:73
	ds_read2_b32 v[118:119], v211 offset0:74 offset1:75
	ds_read2_b32 v[120:121], v211 offset0:80 offset1:81
	ds_read2_b32 v[122:123], v211 offset0:82 offset1:83
	ds_read2_b32 v[124:125], v211 offset0:88 offset1:89
	ds_read2_b32 v[126:127], v211 offset0:90 offset1:91
	ds_read2_b32 v[140:141], v211 offset0:96 offset1:97
	ds_read2_b32 v[142:143], v211 offset0:98 offset1:99
	ds_read2_b32 v[218:219], v211 offset0:104 offset1:105
	ds_read2_b32 v[220:221], v211 offset0:106 offset1:107
	s_waitcnt lgkmcnt(0)
	v_pk_add_f32 v[96:97], v[96:97], v[112:113]
	v_pk_add_f32 v[108:109], v[108:109], v[124:125]
	v_pk_add_f32 v[106:107], v[106:107], v[122:123]
	v_pk_add_f32 v[104:105], v[104:105], v[120:121]
	ds_read2_b32 v[112:113], v211 offset0:112 offset1:113
	ds_read2_b32 v[120:121], v211 offset0:114 offset1:115
	ds_read2_b32 v[122:123], v211 offset0:120 offset1:121
	ds_read2_b32 v[124:125], v211 offset0:122 offset1:123
	v_pk_add_f32 v[110:111], v[110:111], v[126:127]
	v_pk_add_f32 v[102:103], v[102:103], v[118:119]
	v_pk_add_f32 v[100:101], v[100:101], v[116:117]
	v_pk_add_f32 v[98:99], v[98:99], v[114:115]
	v_pk_add_f32 v[80:81], v[80:81], v[140:141]
	s_waitcnt lgkmcnt(0)
	v_pk_add_f32 v[94:95], v[94:95], v[124:125]
	v_pk_add_f32 v[92:93], v[92:93], v[122:123]
	v_pk_add_f32 v[90:91], v[90:91], v[120:121]
	v_pk_add_f32 v[88:89], v[88:89], v[112:113]
	v_pk_add_f32 v[86:87], v[86:87], v[220:221]
	v_pk_add_f32 v[84:85], v[84:85], v[218:219]
	v_pk_add_f32 v[82:83], v[82:83], v[142:143]
	v_mov_b32_e32 v212, 0

; #define SBAR() __builtin_amdgcn_sched_barrier(0)
; __device__ __forceinline__ s16x4 vtr(lds_cptr p) { return __builtin_bit_cast(s16x4, __builtin_amdgcn_ds_read_tr16_b64_v4i16((__attribute__((address_space(3))) v4i16_t*)p)); }
; #define PIN(x) asm volatile("" : "+v"(x))
; __device__ __forceinline__ void add_bias(f32x16& p0, f32x16& p1, const float* tb, int relb, int hi) {
;   const float* t = tb + relb + 4 * hi;
; #pragma unroll
;   for (int r = 0; r < 16; ++r) { p0[r] += t[(r & 3) + 8 * (r >> 2)]; p1[r] += t[32 + (r & 3) + 8 * (r >> 2)]; }
; }
; template <int DK, bool NOMAX> ...
;     ...
;   for (int d0 = 0; d0 < NS; ++d0) {
;     if (d0 == 0) { c0 = __builtin_amdgcn_mfma_f32_32x32x16_bf16(kf[0][0], qr[0], f32x16{}, 0, 0, 0); c1 = __builtin_amdgcn_mfma_f32_32x32x16_bf16(kf[0][1], qr[0], f32x16{}, 0, 0, 0); }
;     else { c0 = __builtin_amdgcn_mfma_f32_32x32x16_bf16(kf[d0 & 1][0], qr[d0], c0, 0, 0, 0); c1 = __builtin_amdgcn_mfma_f32_32x32x16_bf16(kf[d0 & 1][1], qr[d0], c1, 0, 0, 0); }
;     if (d0 + 2 < NS) KRD_(d0 & 1, d0 + 2);
;     if constexpr (NOMAX) { }
;     else {
; #pragma unroll
;     for (int r = d0 * RPS; r < (d0 + 1) * RPS; ++r) { p1[r] = __builtin_amdgcn_exp2f(p1[r]); psa += p0[r]; }
;     if (d0 > 0) {
; #pragma unroll
;       for (int r = (d0 - 1) * RPS; r < d0 * RPS; ++r) psb += p1[r]; } }
;     if constexpr (NOMAX) {
;       if (d0 == NS / 4 - 1) { PK4R(p0, 0, pa[0]); PIN(pa[0]); }
;       if (d0 == NS / 2 - 1) { PK4R(p0, 8, pa[1]); PIN(pa[1]); }
;       if (d0 == 3 * NS / 4 - 1) { PK4R(p1, 0, pa[2]); PIN(pa[2]); }
;       if (d0 == NS - 1) { PK4R(p1, 8, pa[3]); PIN(pa[3]); }
;     } else {
;     if (d0 == NS / 2 - 1) { PK4R(p0, 0, pa[0]); PIN(pa[0]); }
;     if (d0 == NS / 2) { PK4R(p0, 8, pa[1]); PIN(pa[1]); }
;     if (d0 == NS - 1) { PK4R(p1, 0, pa[2]); PIN(pa[2]); }
;     }
;     if (d0 == NS - 1) {
;       vl[0] = vtr(vp + v_rd_off(0, 0, 0)); vh[0] = vtr(vp + v_rd_off(0, 0, 1)); vl[1] = vtr(vp + v_rd_off(1, 0, 0)); vh[1] = vtr(vp + v_rd_off(1, 0, 1)); }
;     PIN(p1); PIN(psa); PIN(psb);
;     SBAR();
;   }
.LBB0_313:
	s_mov_b32 s58, s95
	s_mov_b32 s95, s4
	s_add_i32 s4, s63, 0xffff4000
	s_and_b32 s59, s4, 0xc000
	s_add_i32 s4, s59, 0
	v_add_u32_e32 v213, s95, v187
	s_waitcnt lgkmcnt(0)
	v_mfma_f32_32x32x16_bf16 v[128:143], v[116:119], v[156:159], 0
	v_add_u32_e32 v0, s4, v207
	ds_read_b128 v[2:5], v0
	ds_read_b128 v[164:167], v0 offset:4096
	v_cvt_pk_bf16_f32 v96, v96, v97
	v_cvt_pk_bf16_f32 v97, v98, v99
	v_cvt_pk_bf16_f32 v98, v100, v101
	v_cvt_pk_bf16_f32 v99, v102, v103
	v_mfma_f32_32x32x16_bf16 v[112:127], v[112:115], v[156:159], 0
	v_permlane32_swap_b32_e32 v96, v98
	v_permlane32_swap_b32_e32 v97, v99
	v_mfma_f32_32x32x16_bf16 v[128:143], v[10:13], v[152:155], v[128:143]
	v_mfma_f32_32x32x16_bf16 v[112:127], v[6:9], v[152:155], v[112:127]
	v_add_u32_e32 v6, s4, v208
	ds_read_b128 v[100:103], v6
	ds_read_b128 v[214:217], v6 offset:4096
	v_cvt_pk_bf16_f32 v10, v104, v105
	v_cvt_pk_bf16_f32 v11, v106, v107
	v_cvt_pk_bf16_f32 v12, v108, v109
	v_cvt_pk_bf16_f32 v13, v110, v111
	s_nop 0
	v_permlane32_swap_b32_e32 v10, v12
	v_permlane32_swap_b32_e32 v11, v13
	s_waitcnt lgkmcnt(3)
	v_mfma_f32_32x32x16_bf16 v[128:143], v[2:5], v[148:151], v[128:143]
	v_cvt_pk_bf16_f32 v6, v80, v81
	v_cvt_pk_bf16_f32 v7, v82, v83
	v_cvt_pk_bf16_f32 v8, v84, v85
	v_cvt_pk_bf16_f32 v9, v86, v87
	s_nop 0
	v_permlane32_swap_b32_e32 v6, v8
	s_waitcnt lgkmcnt(2)
	v_mfma_f32_32x32x16_bf16 v[112:127], v[164:167], v[148:151], v[112:127]
	v_permlane32_swap_b32_e32 v7, v9
	s_nop 0
	v_cvt_pk_bf16_f32 v2, v88, v89
	v_cvt_pk_bf16_f32 v3, v90, v91
	v_cvt_pk_bf16_f32 v4, v92, v93
	v_cvt_pk_bf16_f32 v5, v94, v95
	s_cmp_gt_i32 s96, 59
	s_cbranch_scc1 .Lmy_mb0_a2_1
	s_waitcnt vmcnt(3) lgkmcnt(0)
	s_barrier
.Lmy_mbj_a2_1:
	ds_read_b64_tr_b16 v[104:105], v213
	ds_read_b64_tr_b16 v[106:107], v213 offset:2048
	v_mfma_f32_32x32x16_bf16 v[128:143], v[100:103], v[144:147], v[128:143]
	v_permlane32_swap_b32_e32 v2, v4
	v_permlane32_swap_b32_e32 v3, v5
	ds_read_b64_tr_b16 v[100:101], v213 offset:512
	ds_read_b64_tr_b16 v[102:103], v213 offset:2560
	s_waitcnt lgkmcnt(4)
	v_mfma_f32_32x32x16_bf16 v[112:127], v[214:217], v[144:147], v[112:127]
	v_add_u32_e32 v216, s94, v205
	v_add_u32_e32 v0, 0xffffffa1, v216
	v_cmp_gt_i32_e32 vcc, s67, v0
	v_mov_b32_e32 v215, v199
	s_and_saveexec_b64 s[4:5], vcc
	s_cbranch_execz .LBB0_317
	v_subrev_u32_e32 v0, 64, v216
	v_cmp_lt_i32_e32 vcc, s77, v0
	v_mov_b32_e32 v215, v198
	s_and_saveexec_b64 s[16:17], vcc
	s_cbranch_execz .LBB0_316
	ds_read2_b32 v[80:81], v211 offset1:1
	ds_read2_b32 v[82:83], v211 offset0:2 offset1:3
	ds_read2_b32 v[84:85], v211 offset0:8 offset1:9
	ds_read2_b32 v[86:87], v211 offset0:10 offset1:11
	ds_read2_b32 v[88:89], v211 offset0:16 offset1:17
	ds_read2_b32 v[90:91], v211 offset0:18 offset1:19
	ds_read2_b32 v[92:93], v211 offset0:24 offset1:25
	ds_read2_b32 v[94:95], v211 offset0:26 offset1:27
	ds_read2_b32 v[108:109], v211 offset0:32 offset1:33
	ds_read2_b32 v[110:111], v211 offset0:34 offset1:35
	ds_read2_b32 v[164:165], v211 offset0:40 offset1:41
	ds_read2_b32 v[166:167], v211 offset0:42 offset1:43
	s_waitcnt lgkmcnt(0)
	v_pk_add_f32 v[128:129], v[128:129], v[80:81]
	v_pk_add_f32 v[140:141], v[140:141], v[92:93]
	v_pk_add_f32 v[138:139], v[138:139], v[90:91]
	v_pk_add_f32 v[136:137], v[136:137], v[88:89]
	ds_read2_b32 v[80:81], v211 offset0:48 offset1:49
	ds_read2_b32 v[88:89], v211 offset0:50 offset1:51
	ds_read2_b32 v[90:91], v211 offset0:56 offset1:57
	ds_read2_b32 v[92:93], v211 offset0:58 offset1:59
	v_pk_add_f32 v[142:143], v[142:143], v[94:95]
	v_pk_add_f32 v[134:135], v[134:135], v[86:87]
	v_pk_add_f32 v[132:133], v[132:133], v[84:85]
	v_pk_add_f32 v[130:131], v[130:131], v[82:83]
	v_pk_add_f32 v[112:113], v[112:113], v[108:109]
	s_waitcnt lgkmcnt(0)
	v_pk_add_f32 v[126:127], v[126:127], v[92:93]
	v_pk_add_f32 v[124:125], v[124:125], v[90:91]
	v_pk_add_f32 v[122:123], v[122:123], v[88:89]
	v_pk_add_f32 v[120:121], v[120:121], v[80:81]
	v_pk_add_f32 v[118:119], v[118:119], v[166:167]
	v_pk_add_f32 v[116:117], v[116:117], v[164:165]
	v_pk_add_f32 v[114:115], v[114:115], v[110:111]
	v_mov_b32_e32 v215, 0

; #define SBAR() __builtin_amdgcn_sched_barrier(0)
; __device__ __forceinline__ s16x4 vtr(lds_cptr p) { return __builtin_bit_cast(s16x4, __builtin_amdgcn_ds_read_tr16_b64_v4i16((__attribute__((address_space(3))) v4i16_t*)p)); }
; #define PIN(x) asm volatile("" : "+v"(x))
; __device__ __forceinline__ void add_bias(f32x16& p0, f32x16& p1, const float* tb, int relb, int hi) {
;   const float* t = tb + relb + 4 * hi;
; #pragma unroll
;   for (int r = 0; r < 16; ++r) { p0[r] += t[(r & 3) + 8 * (r >> 2)]; p1[r] += t[32 + (r & 3) + 8 * (r >> 2)]; }
; }
; template <int DK, bool NOMAX> ...
;     ...
;   for (int d0 = 0; d0 < NS; ++d0) {
;     if (d0 == 0) { c0 = __builtin_amdgcn_mfma_f32_32x32x16_bf16(kf[0][0], qr[0], f32x16{}, 0, 0, 0); c1 = __builtin_amdgcn_mfma_f32_32x32x16_bf16(kf[0][1], qr[0], f32x16{}, 0, 0, 0); }
;     else { c0 = __builtin_amdgcn_mfma_f32_32x32x16_bf16(kf[d0 & 1][0], qr[d0], c0, 0, 0, 0); c1 = __builtin_amdgcn_mfma_f32_32x32x16_bf16(kf[d0 & 1][1], qr[d0], c1, 0, 0, 0); }
;     if (d0 + 2 < NS) KRD_(d0 & 1, d0 + 2);
;     if constexpr (NOMAX) { }
;     else {
; #pragma unroll
;     for (int r = d0 * RPS; r < (d0 + 1) * RPS; ++r) { p1[r] = __builtin_amdgcn_exp2f(p1[r]); psa += p0[r]; }
;     if (d0 > 0) {
; #pragma unroll
;       for (int r = (d0 - 1) * RPS; r < d0 * RPS; ++r) psb += p1[r]; } }
;     if constexpr (NOMAX) {
;       if (d0 == NS / 4 - 1) { PK4R(p0, 0, pa[0]); PIN(pa[0]); }
;       if (d0 == NS / 2 - 1) { PK4R(p0, 8, pa[1]); PIN(pa[1]); }
;       if (d0 == 3 * NS / 4 - 1) { PK4R(p1, 0, pa[2]); PIN(pa[2]); }
;       if (d0 == NS - 1) { PK4R(p1, 8, pa[3]); PIN(pa[3]); }
;     } else {
;     if (d0 == NS / 2 - 1) { PK4R(p0, 0, pa[0]); PIN(pa[0]); }
;     if (d0 == NS / 2) { PK4R(p0, 8, pa[1]); PIN(pa[1]); }
;     if (d0 == NS - 1) { PK4R(p1, 0, pa[2]); PIN(pa[2]); }
;     }
;     if (d0 == NS - 1) {
;       vl[0] = vtr(vp + v_rd_off(0, 0, 0)); vh[0] = vtr(vp + v_rd_off(0, 0, 1)); vl[1] = vtr(vp + v_rd_off(1, 0, 0)); vh[1] = vtr(vp + v_rd_off(1, 0, 1)); }
;     PIN(p1); PIN(psa); PIN(psb);
;     SBAR();
;   }
.LBB0_325:
.LBB0_327:
	v_add_u32_e32 v217, s58, v187
	v_mfma_f32_32x32x16_bf16 v[96:111], v[80:83], v[156:159], 0
	v_add_u32_e32 v212, s18, v207
	ds_read_b128 v[2:5], v212
	ds_read_b128 v[218:221], v212 offset:4096
	v_cvt_pk_bf16_f32 v128, v128, v129
	v_cvt_pk_bf16_f32 v129, v130, v131
	v_cvt_pk_bf16_f32 v130, v132, v133
	v_cvt_pk_bf16_f32 v131, v134, v135
	v_mfma_f32_32x32x16_bf16 v[80:95], v[84:87], v[156:159], 0
	v_permlane32_swap_b32_e32 v128, v130
	v_permlane32_swap_b32_e32 v129, v131
	v_mfma_f32_32x32x16_bf16 v[96:111], v[6:9], v[152:155], v[96:111]
	v_add_u32_e32 v6, s18, v208
	ds_read_b128 v[132:135], v6
	ds_read_b128 v[222:225], v6 offset:4096
	v_mfma_f32_32x32x16_bf16 v[80:95], v[10:13], v[152:155], v[80:95]
	v_cvt_pk_bf16_f32 v10, v136, v137
	v_cvt_pk_bf16_f32 v11, v138, v139
	v_cvt_pk_bf16_f32 v12, v140, v141
	v_cvt_pk_bf16_f32 v13, v142, v143
	s_nop 0
	v_permlane32_swap_b32_e32 v10, v12
	v_permlane32_swap_b32_e32 v11, v13
	s_waitcnt lgkmcnt(3)
	v_mfma_f32_32x32x16_bf16 v[96:111], v[2:5], v[148:151], v[96:111]
	v_cvt_pk_bf16_f32 v6, v112, v113
	v_cvt_pk_bf16_f32 v7, v114, v115
	v_cvt_pk_bf16_f32 v8, v116, v117
	v_cvt_pk_bf16_f32 v9, v118, v119
	s_nop 0
	v_permlane32_swap_b32_e32 v6, v8
	s_waitcnt lgkmcnt(2)
	v_mfma_f32_32x32x16_bf16 v[80:95], v[218:221], v[148:151], v[80:95]
	v_permlane32_swap_b32_e32 v7, v9
	s_nop 0
	v_cvt_pk_bf16_f32 v2, v120, v121
	v_cvt_pk_bf16_f32 v3, v122, v123
	v_cvt_pk_bf16_f32 v4, v124, v125
	v_cvt_pk_bf16_f32 v5, v126, v127
	s_cmp_gt_i32 s96, 60
	s_cbranch_scc1 .Lmy_mb0_a2_2
	s_waitcnt vmcnt(3) lgkmcnt(0)
	s_barrier
.Lmy_mbj_a2_2:
	ds_read_b64_tr_b16 v[136:137], v217
	ds_read_b64_tr_b16 v[138:139], v217 offset:2048
	v_mfma_f32_32x32x16_bf16 v[96:111], v[132:135], v[144:147], v[96:111]
	v_permlane32_swap_b32_e32 v2, v4
	v_permlane32_swap_b32_e32 v3, v5
	ds_read_b64_tr_b16 v[132:133], v217 offset:512
	ds_read_b64_tr_b16 v[134:135], v217 offset:2560
	s_waitcnt lgkmcnt(4)
	v_mfma_f32_32x32x16_bf16 v[80:95], v[222:225], v[144:147], v[80:95]
	v_subrev_u32_e32 v112, 31, v216
	v_cmp_gt_i32_e32 vcc, s67, v112
	v_mov_b32_e32 v212, v199
	s_and_saveexec_b64 s[4:5], vcc
	s_cbranch_execz .LBB0_331
	v_cmp_ge_i32_e32 vcc, s94, v181
	v_mov_b32_e32 v212, v198
	s_and_saveexec_b64 s[18:19], vcc
	s_cbranch_execz .LBB0_330
	ds_read2_b32 v[112:113], v211 offset0:64 offset1:65
	ds_read2_b32 v[114:115], v211 offset0:66 offset1:67
	ds_read2_b32 v[116:117], v211 offset0:72 offset1:73
	ds_read2_b32 v[118:119], v211 offset0:74 offset1:75
	ds_read2_b32 v[120:121], v211 offset0:80 offset1:81
	ds_read2_b32 v[122:123], v211 offset0:82 offset1:83
	ds_read2_b32 v[124:125], v211 offset0:88 offset1:89
	ds_read2_b32 v[126:127], v211 offset0:90 offset1:91
	ds_read2_b32 v[140:141], v211 offset0:96 offset1:97
	ds_read2_b32 v[142:143], v211 offset0:98 offset1:99
	ds_read2_b32 v[218:219], v211 offset0:104 offset1:105
	ds_read2_b32 v[220:221], v211 offset0:106 offset1:107
	s_waitcnt lgkmcnt(0)
	v_pk_add_f32 v[96:97], v[96:97], v[112:113]
	v_pk_add_f32 v[108:109], v[108:109], v[124:125]
	v_pk_add_f32 v[106:107], v[106:107], v[122:123]
	v_pk_add_f32 v[104:105], v[104:105], v[120:121]
	ds_read2_b32 v[112:113], v211 offset0:112 offset1:113
	ds_read2_b32 v[120:121], v211 offset0:114 offset1:115
	ds_read2_b32 v[122:123], v211 offset0:120 offset1:121
	ds_read2_b32 v[124:125], v211 offset0:122 offset1:123
	v_pk_add_f32 v[110:111], v[110:111], v[126:127]
	v_pk_add_f32 v[102:103], v[102:103], v[118:119]
	v_pk_add_f32 v[100:101], v[100:101], v[116:117]
	v_pk_add_f32 v[98:99], v[98:99], v[114:115]
	v_pk_add_f32 v[80:81], v[80:81], v[140:141]
	s_waitcnt lgkmcnt(0)
	v_pk_add_f32 v[94:95], v[94:95], v[124:125]
	v_pk_add_f32 v[92:93], v[92:93], v[122:123]
	v_pk_add_f32 v[90:91], v[90:91], v[120:121]
	v_pk_add_f32 v[88:89], v[88:89], v[112:113]
	v_pk_add_f32 v[86:87], v[86:87], v[220:221]
	v_pk_add_f32 v[84:85], v[84:85], v[218:219]
	v_pk_add_f32 v[82:83], v[82:83], v[142:143]
	v_mov_b32_e32 v212, 0
